# out-proj fused epilogue: x residual loads of row groups 4..7 batched into dead prefetch registers + L2 warm-up before the exchange (was 16 serialized load->vmcnt(0) round trips)
# baseline (speedup 1.0000x reference)
.LBB0_228:
	s_lshl_b32 s2, s38, 5
	s_lshl_b32 s3, s18, 8
	s_or_b32 s2, s3, s2
	v_lshrrev_b32_e32 v122, 2, v210
	s_lshl_b32 s30, s29, 8
	v_and_or_b32 v214, v122, 12, s2
	s_add_i32 s2, s30, s28
	v_or_b32_e32 v122, s2, v219
	v_ashrrev_i32_e32 v215, 31, v214
	v_lshlrev_b64 v[124:125], 2, v[214:215]
	v_ashrrev_i32_e32 v123, 31, v122
	v_lshl_add_u64 v[216:217], s[0:1], 0, v[124:125]
	v_lshlrev_b64 v[130:131], 12, v[122:123]
	v_lshl_add_u64 v[130:131], v[216:217], 0, v[130:131]
	s_barrier
	global_load_dwordx4 v[206:209], v[130:131], off
	global_load_dwordx4 v[202:205], v[130:131], off offset:64
	global_load_dwordx4 v[198:201], v[130:131], off offset:512
	global_load_dwordx4 v[194:197], v[130:131], off offset:576
	v_or_b32_e32 v130, 16, v122
	v_ashrrev_i32_e32 v131, 31, v130
	v_lshlrev_b64 v[130:131], 12, v[130:131]
	v_lshl_add_u64 v[130:131], v[216:217], 0, v[130:131]
	global_load_dwordx4 v[190:193], v[130:131], off
	global_load_dwordx4 v[186:189], v[130:131], off offset:64
	global_load_dwordx4 v[182:185], v[130:131], off offset:512
	global_load_dwordx4 v[178:181], v[130:131], off offset:576
	v_or_b32_e32 v130, 32, v122
	v_or_b32_e32 v122, 48, v122
	v_ashrrev_i32_e32 v131, 31, v130
	v_ashrrev_i32_e32 v123, 31, v122
	v_lshlrev_b64 v[130:131], 12, v[130:131]
	v_lshlrev_b64 v[122:123], 12, v[122:123]
	v_lshl_add_u64 v[130:131], v[216:217], 0, v[130:131]
	v_lshl_add_u64 v[122:123], v[216:217], 0, v[122:123]
	global_load_dwordx4 v[174:177], v[130:131], off
	global_load_dwordx4 v[170:173], v[130:131], off offset:64
	global_load_dwordx4 v[166:169], v[130:131], off offset:512
	global_load_dwordx4 v[162:165], v[130:131], off offset:576
	global_load_dwordx4 v[158:161], v[122:123], off
	global_load_dwordx4 v[154:157], v[122:123], off offset:64
	global_load_dwordx4 v[150:153], v[122:123], off offset:512
	global_load_dwordx4 v[146:149], v[122:123], off offset:576
	v_lshl_add_u64 v[122:123], s[22:23], 0, v[124:125]
	global_load_dwordx4 v[142:145], v[122:123], off
	global_load_dwordx4 v[134:137], v[122:123], off offset:64
	global_load_dwordx4 v[130:133], v[122:123], off offset:512
	s_nop 0
	global_load_dwordx4 v[122:125], v[122:123], off offset:576
	v_mov_b32_e32 v238, s28
	v_add_u32_e32 v238, 0x80, v238
	v_or_b32_e32 v234, v238, v219
	v_add_u32_e32 v234, s30, v234
	v_ashrrev_i32_e32 v235, 31, v234
	v_lshlrev_b64 v[234:235], 12, v[234:235]
	v_lshl_add_u64 v[234:235], v[216:217], 0, v[234:235]
	v_mov_b32_e32 v238, 0x10000
	v_mov_b32_e32 v239, 0
	v_mov_b32_e32 v236, v234
	v_mov_b32_e32 v237, v235
	global_load_dwordx4 v[240:243], v[236:237], off
	global_load_dwordx4 v[240:243], v[236:237], off offset:64
	global_load_dwordx4 v[240:243], v[236:237], off offset:512
	global_load_dwordx4 v[240:243], v[236:237], off offset:576
	v_lshl_add_u64 v[236:237], v[236:237], 0, v[238:239]
	global_load_dwordx4 v[240:243], v[236:237], off
	global_load_dwordx4 v[240:243], v[236:237], off offset:64
	global_load_dwordx4 v[240:243], v[236:237], off offset:512
	global_load_dwordx4 v[240:243], v[236:237], off offset:576
	v_lshl_add_u64 v[236:237], v[236:237], 0, v[238:239]
	global_load_dwordx4 v[240:243], v[236:237], off
	global_load_dwordx4 v[240:243], v[236:237], off offset:64
	global_load_dwordx4 v[240:243], v[236:237], off offset:512
	global_load_dwordx4 v[240:243], v[236:237], off offset:576
	v_lshl_add_u64 v[236:237], v[236:237], 0, v[238:239]
	global_load_dwordx4 v[240:243], v[236:237], off
	global_load_dwordx4 v[240:243], v[236:237], off offset:64
	global_load_dwordx4 v[240:243], v[236:237], off offset:512
	global_load_dwordx4 v[240:243], v[236:237], off offset:576
	v_mul_f32_e32 v211, v139, v139
	v_mul_f32_e32 v212, v141, v141
	v_fmac_f32_e32 v211, v138, v138
	v_fmac_f32_e32 v212, v140, v140
	v_add_f32_e32 v211, v211, v212
	v_mul_f32_e32 v212, v127, v127
	v_mul_f32_e32 v213, v129, v129
	v_fmac_f32_e32 v212, v126, v126
	v_fmac_f32_e32 v213, v128, v128
	v_add_f32_e32 v212, v212, v213
	v_add_f32_e32 v211, v212, v211
	v_mul_f32_e32 v212, v119, v119
	v_mul_f32_e32 v213, v121, v121
	v_fmac_f32_e32 v212, v118, v118
	v_fmac_f32_e32 v213, v120, v120
	v_add_f32_e32 v212, v212, v213
	v_add_f32_e32 v211, v212, v211
	v_mul_f32_e32 v212, v115, v115
	v_mul_f32_e32 v213, v117, v117
	v_fmac_f32_e32 v212, v114, v114
	v_fmac_f32_e32 v213, v116, v116
	v_add_f32_e32 v212, v212, v213
	v_add_f32_e32 v211, v212, v211
	ds_bpermute_b32 v212, v1, v211
	v_and_b32_e32 v226, 63, v210
	s_lshl_b32 s0, s38, 2
	v_cmp_gt_u32_e64 s[4:5], 16, v226
	s_add_i32 s31, s0, 0
	s_waitcnt lgkmcnt(0)
	v_add_f32_e32 v211, v211, v212
	ds_bpermute_b32 v212, v233, v211
	s_and_saveexec_b64 s[0:1], s[4:5]
	s_cbranch_execz .LBB0_230
	s_lshl_b32 s2, s24, 10
	s_add_i32 s2, s31, s2
	v_lshl_add_u32 v213, v219, 4, s2
	s_waitcnt lgkmcnt(0)
	v_add_f32_e32 v211, v211, v212
	ds_write_b32 v213, v211

.LBB0_258:
	s_or_b64 exec, exec, s[0:1]
	s_waitcnt vmcnt(0) lgkmcnt(0)
	s_barrier
	v_mov_b32_e32 v210, 0
	ds_read_b32 v211, v210 offset:10240
	v_lshl_add_u32 v210, v225, 2, 0
	s_waitcnt lgkmcnt(0)
	ds_read_b32 v212, v210 offset:8192
	v_add_u32_e32 v220, s30, v225
	s_add_u32 s0, s16, 0x3000000
	s_waitcnt vmcnt(20)
	v_or_b32_e32 v211, v211, v224
	v_ashrrev_i32_e32 v221, 31, v220
	s_waitcnt lgkmcnt(0)
	v_pk_mul_f32 v[138:139], v[138:139], v[212:213] op_sel_hi:[1,0]
	v_pk_mul_f32 v[140:141], v[140:141], v[212:213] op_sel_hi:[1,0]
	s_waitcnt vmcnt(3)
	v_pk_fma_f32 v[206:207], v[142:143], v[138:139], v[206:207]
	v_mov_b32_e32 v138, 0x7fc00000
	v_cmp_ne_u32_e32 vcc, 0, v211
	s_addc_u32 s1, s17, 0
	v_pk_fma_f32 v[140:141], v[144:145], v[140:141], v[208:209]
	v_cndmask_b32_e32 v209, v206, v138, vcc
	v_cndmask_b32_e32 v211, v207, v138, vcc
	v_lshlrev_b64 v[206:207], 11, v[220:221]
	v_lshl_add_u64 v[206:207], s[0:1], 0, v[206:207]
	v_cndmask_b32_e32 v139, v140, v138, vcc
	v_cndmask_b32_e32 v208, v141, v138, vcc
	v_cvt_pk_bf16_f32 v140, v209, v211
	v_cvt_pk_bf16_f32 v141, v139, v208
	v_lshl_add_u64 v[206:207], v[214:215], 1, v[206:207]
	v_pk_mul_f32 v[126:127], v[126:127], v[212:213] op_sel_hi:[1,0]
	global_store_dwordx2 v[206:207], v[140:141], off
	v_mul_f32_e32 v140, v211, v211
	v_mul_f32_e32 v141, v208, v208
	v_pk_mul_f32 v[128:129], v[128:129], v[212:213] op_sel_hi:[1,0]
	s_waitcnt vmcnt(3)
	v_pk_fma_f32 v[126:127], v[134:135], v[126:127], v[202:203]
	v_fmac_f32_e32 v140, v209, v209
	v_fmac_f32_e32 v141, v139, v139
	v_pk_fma_f32 v[128:129], v[136:137], v[128:129], v[204:205]
	v_cndmask_b32_e32 v127, v127, v138, vcc
	v_add_f32_e32 v139, v140, v141
	v_cndmask_b32_e32 v129, v129, v138, vcc
	v_cndmask_b32_e32 v140, v126, v138, vcc
	v_cvt_pk_bf16_f32 v126, v140, v127
	v_mul_f32_e32 v127, v127, v127
	v_cndmask_b32_e32 v128, v128, v138, vcc
	v_fmac_f32_e32 v127, v140, v140
	v_mul_f32_e32 v140, v129, v129
	v_pk_mul_f32 v[120:121], v[120:121], v[212:213] op_sel_hi:[1,0]
	v_pk_mul_f32 v[118:119], v[118:119], v[212:213] op_sel_hi:[1,0]
	v_fmac_f32_e32 v140, v128, v128
	s_waitcnt vmcnt(2)
	v_pk_fma_f32 v[118:119], v[130:131], v[118:119], v[198:199]
	v_pk_fma_f32 v[120:121], v[132:133], v[120:121], v[200:201]
	v_add_f32_e32 v127, v127, v140
	v_cndmask_b32_e32 v121, v121, v138, vcc
	v_cndmask_b32_e32 v119, v119, v138, vcc
	v_add_f32_e32 v127, v139, v127
	v_cndmask_b32_e32 v120, v120, v138, vcc
	v_cndmask_b32_e32 v118, v118, v138, vcc
	v_mul_f32_e32 v139, v119, v119
	v_mul_f32_e32 v140, v121, v121
	v_pk_mul_f32 v[116:117], v[116:117], v[212:213] op_sel_hi:[1,0]
	v_pk_mul_f32 v[114:115], v[114:115], v[212:213] op_sel_hi:[1,0]
	v_fmac_f32_e32 v139, v118, v118
	v_fmac_f32_e32 v140, v120, v120
	s_waitcnt vmcnt(1)
	v_pk_fma_f32 v[114:115], v[122:123], v[114:115], v[194:195]
	v_pk_fma_f32 v[116:117], v[124:125], v[116:117], v[196:197]
	v_add_f32_e32 v139, v139, v140
	v_cndmask_b32_e32 v140, v117, v138, vcc
	v_cndmask_b32_e32 v194, v115, v138, vcc
	v_add_f32_e32 v127, v139, v127
	v_cndmask_b32_e32 v139, v116, v138, vcc
	v_cndmask_b32_e32 v141, v114, v138, vcc
	v_mul_f32_e32 v114, v194, v194
	v_mul_f32_e32 v115, v140, v140
	v_fmac_f32_e32 v114, v141, v141
	v_fmac_f32_e32 v115, v139, v139
	v_add_f32_e32 v114, v114, v115
	v_add_f32_e32 v114, v114, v127
	ds_bpermute_b32 v115, v1, v114
	v_cvt_pk_bf16_f32 v127, v128, v129
	global_store_dwordx2 v[206:207], v[126:127], off offset:32
	v_cvt_pk_bf16_f32 v116, v118, v119
	v_cvt_pk_bf16_f32 v117, v120, v121
	s_waitcnt lgkmcnt(0)
	v_add_f32_e32 v114, v114, v115
	ds_bpermute_b32 v115, v233, v114
	global_store_dwordx2 v[206:207], v[116:117], off offset:256
	v_cvt_pk_bf16_f32 v116, v141, v194
	v_cvt_pk_bf16_f32 v117, v139, v140
	global_store_dwordx2 v[206:207], v[116:117], off offset:288
	v_mov_b32_e32 v236, v234
	v_mov_b32_e32 v237, v235
	global_load_dwordx4 v[194:197], v[236:237], off
	global_load_dwordx4 v[198:201], v[236:237], off offset:64
	global_load_dwordx4 v[202:205], v[236:237], off offset:512
	global_load_dwordx4 v[206:209], v[236:237], off offset:576
	s_and_saveexec_b64 s[2:3], s[4:5]
	s_cbranch_execz .LBB0_260
	v_lshl_add_u32 v116, v225, 4, s31
	s_waitcnt lgkmcnt(0)
	v_add_f32_e32 v114, v114, v115
	ds_write_b32 v116, v114 offset:16384
.LBB0_260:
	s_or_b64 exec, exec, s[2:3]
	ds_read_b32 v116, v210 offset:8256
	v_or_b32_e32 v114, 16, v225
	v_add_u32_e32 v118, s30, v114
	v_ashrrev_i32_e32 v119, 31, v118
	s_waitcnt lgkmcnt(0)
	v_pk_mul_f32 v[112:113], v[112:113], v[116:117] op_sel_hi:[1,0]
	s_nop 0
	v_pk_fma_f32 v[112:113], v[144:145], v[112:113], v[192:193]
	v_pk_mul_f32 v[110:111], v[110:111], v[116:117] op_sel_hi:[1,0]
	v_cndmask_b32_e32 v115, v112, v138, vcc
	v_cndmask_b32_e32 v117, v113, v138, vcc
	v_lshlrev_b64 v[112:113], 11, v[118:119]
	v_pk_fma_f32 v[110:111], v[142:143], v[110:111], v[190:191]
	v_lshl_add_u64 v[112:113], s[0:1], 0, v[112:113]
	v_cndmask_b32_e32 v120, v110, v138, vcc
	v_cndmask_b32_e32 v121, v111, v138, vcc
	v_cvt_pk_bf16_f32 v110, v120, v121
	v_cvt_pk_bf16_f32 v111, v115, v117
	v_lshl_add_u64 v[112:113], v[214:215], 1, v[112:113]
	v_pk_mul_f32 v[106:107], v[106:107], v[116:117] op_sel_hi:[1,0]
	global_store_dwordx2 v[112:113], v[110:111], off
	v_mul_f32_e32 v110, v121, v121
	v_mul_f32_e32 v111, v117, v117
	v_pk_mul_f32 v[108:109], v[108:109], v[116:117] op_sel_hi:[1,0]
	v_pk_fma_f32 v[106:107], v[134:135], v[106:107], v[186:187]
	v_fmac_f32_e32 v110, v120, v120
	v_fmac_f32_e32 v111, v115, v115
	v_pk_fma_f32 v[108:109], v[136:137], v[108:109], v[188:189]
	v_cndmask_b32_e32 v107, v107, v138, vcc
	v_add_f32_e32 v110, v110, v111
	v_cndmask_b32_e32 v109, v109, v138, vcc
	v_cndmask_b32_e32 v111, v106, v138, vcc
	v_cvt_pk_bf16_f32 v106, v111, v107
	v_mul_f32_e32 v107, v107, v107
	v_cndmask_b32_e32 v108, v108, v138, vcc
	v_fmac_f32_e32 v107, v111, v111
	v_mul_f32_e32 v111, v109, v109
	v_pk_mul_f32 v[104:105], v[104:105], v[116:117] op_sel_hi:[1,0]
	v_pk_mul_f32 v[102:103], v[102:103], v[116:117] op_sel_hi:[1,0]
	v_fmac_f32_e32 v111, v108, v108
	v_pk_fma_f32 v[104:105], v[132:133], v[104:105], v[184:185]
	v_pk_fma_f32 v[102:103], v[130:131], v[102:103], v[182:183]
	v_add_f32_e32 v107, v107, v111
	v_cndmask_b32_e32 v105, v105, v138, vcc
	v_cndmask_b32_e32 v103, v103, v138, vcc
	v_add_f32_e32 v107, v110, v107
	v_cndmask_b32_e32 v104, v104, v138, vcc
	v_cndmask_b32_e32 v102, v102, v138, vcc
	v_mul_f32_e32 v110, v103, v103
	v_mul_f32_e32 v111, v105, v105
	v_pk_mul_f32 v[100:101], v[100:101], v[116:117] op_sel_hi:[1,0]
	v_pk_mul_f32 v[98:99], v[98:99], v[116:117] op_sel_hi:[1,0]
	v_fmac_f32_e32 v110, v102, v102
	v_fmac_f32_e32 v111, v104, v104
	v_pk_fma_f32 v[100:101], v[124:125], v[100:101], v[180:181]
	v_pk_fma_f32 v[98:99], v[122:123], v[98:99], v[178:179]
	v_add_f32_e32 v110, v110, v111
	v_cndmask_b32_e32 v111, v101, v138, vcc
	v_cndmask_b32_e32 v116, v99, v138, vcc
	v_add_f32_e32 v107, v110, v107
	v_cndmask_b32_e32 v110, v100, v138, vcc
	v_cndmask_b32_e32 v115, v98, v138, vcc
	v_mul_f32_e32 v98, v116, v116
	v_mul_f32_e32 v99, v111, v111
	v_fmac_f32_e32 v98, v115, v115
	v_fmac_f32_e32 v99, v110, v110
	v_add_f32_e32 v98, v98, v99
	v_add_f32_e32 v98, v98, v107
	ds_bpermute_b32 v99, v1, v98
	v_cvt_pk_bf16_f32 v107, v108, v109
	global_store_dwordx2 v[112:113], v[106:107], off offset:32
	v_cvt_pk_bf16_f32 v100, v102, v103
	v_cvt_pk_bf16_f32 v101, v104, v105
	s_waitcnt lgkmcnt(0)
	v_add_f32_e32 v98, v98, v99
	ds_bpermute_b32 v99, v233, v98
	global_store_dwordx2 v[112:113], v[100:101], off offset:256
	v_cvt_pk_bf16_f32 v100, v115, v116
	v_cvt_pk_bf16_f32 v101, v110, v111
	global_store_dwordx2 v[112:113], v[100:101], off offset:288
	v_lshl_add_u64 v[236:237], v[236:237], 0, v[238:239]
	global_load_dwordx4 v[178:181], v[236:237], off
	global_load_dwordx4 v[182:185], v[236:237], off offset:64
	global_load_dwordx4 v[186:189], v[236:237], off offset:512
	global_load_dwordx4 v[190:193], v[236:237], off offset:576
	s_and_saveexec_b64 s[2:3], s[4:5]
	s_cbranch_execz .LBB0_262
	v_lshl_add_u32 v100, v114, 4, s31
	s_waitcnt lgkmcnt(0)
	v_add_f32_e32 v98, v98, v99
	ds_write_b32 v100, v98 offset:16384
.LBB0_262:
	s_or_b64 exec, exec, s[2:3]
	ds_read_b32 v100, v210 offset:8320
	v_or_b32_e32 v98, 32, v225
	v_add_u32_e32 v102, s30, v98
	v_ashrrev_i32_e32 v103, 31, v102
	v_lshlrev_b64 v[102:103], 11, v[102:103]
	s_waitcnt lgkmcnt(0)
	v_pk_mul_f32 v[94:95], v[94:95], v[100:101] op_sel_hi:[1,0]
	v_pk_mul_f32 v[96:97], v[96:97], v[100:101] op_sel_hi:[1,0]
	v_pk_fma_f32 v[104:105], v[142:143], v[94:95], v[174:175]
	v_mov_b32_e32 v94, 0x7fc00000
	v_pk_fma_f32 v[96:97], v[144:145], v[96:97], v[176:177]
	v_cndmask_b32_e32 v101, v104, v94, vcc
	v_lshl_add_u64 v[102:103], s[0:1], 0, v[102:103]
	v_cndmask_b32_e32 v95, v96, v94, vcc
	v_cndmask_b32_e32 v99, v97, v94, vcc
	v_cndmask_b32_e32 v104, v105, v94, vcc
	v_cvt_pk_bf16_f32 v96, v101, v104
	v_cvt_pk_bf16_f32 v97, v95, v99
	v_lshl_add_u64 v[102:103], v[214:215], 1, v[102:103]
	v_pk_mul_f32 v[90:91], v[90:91], v[100:101] op_sel_hi:[1,0]
	global_store_dwordx2 v[102:103], v[96:97], off
	v_mul_f32_e32 v96, v104, v104
	v_mul_f32_e32 v97, v99, v99
	v_pk_mul_f32 v[92:93], v[92:93], v[100:101] op_sel_hi:[1,0]
	v_pk_fma_f32 v[90:91], v[134:135], v[90:91], v[170:171]
	v_fmac_f32_e32 v96, v101, v101
	v_fmac_f32_e32 v97, v95, v95
	v_pk_fma_f32 v[92:93], v[136:137], v[92:93], v[172:173]
	v_cndmask_b32_e32 v91, v91, v94, vcc
	v_add_f32_e32 v95, v96, v97
	v_cndmask_b32_e32 v93, v93, v94, vcc
	v_cndmask_b32_e32 v96, v90, v94, vcc
	v_cvt_pk_bf16_f32 v90, v96, v91
	v_mul_f32_e32 v91, v91, v91
	v_cndmask_b32_e32 v92, v92, v94, vcc
	v_fmac_f32_e32 v91, v96, v96
	v_mul_f32_e32 v96, v93, v93
	v_pk_mul_f32 v[88:89], v[88:89], v[100:101] op_sel_hi:[1,0]
	v_pk_mul_f32 v[86:87], v[86:87], v[100:101] op_sel_hi:[1,0]
	v_fmac_f32_e32 v96, v92, v92
	v_pk_fma_f32 v[88:89], v[132:133], v[88:89], v[168:169]
	v_pk_fma_f32 v[86:87], v[130:131], v[86:87], v[166:167]
	v_add_f32_e32 v91, v91, v96
	v_cndmask_b32_e32 v89, v89, v94, vcc
	v_cndmask_b32_e32 v87, v87, v94, vcc
	v_add_f32_e32 v91, v95, v91
	v_cndmask_b32_e32 v88, v88, v94, vcc
	v_cndmask_b32_e32 v86, v86, v94, vcc
	v_mul_f32_e32 v95, v87, v87
	v_mul_f32_e32 v96, v89, v89
	v_pk_mul_f32 v[84:85], v[84:85], v[100:101] op_sel_hi:[1,0]
	v_pk_mul_f32 v[82:83], v[82:83], v[100:101] op_sel_hi:[1,0]
	v_fmac_f32_e32 v95, v86, v86
	v_fmac_f32_e32 v96, v88, v88
	v_pk_fma_f32 v[84:85], v[124:125], v[84:85], v[164:165]
	v_pk_fma_f32 v[82:83], v[122:123], v[82:83], v[162:163]
	v_add_f32_e32 v95, v95, v96
	v_cndmask_b32_e32 v96, v85, v94, vcc
	v_cndmask_b32_e32 v99, v83, v94, vcc
	v_add_f32_e32 v91, v95, v91
	v_cndmask_b32_e32 v95, v84, v94, vcc
	v_cndmask_b32_e32 v97, v82, v94, vcc
	v_mul_f32_e32 v82, v99, v99
	v_mul_f32_e32 v83, v96, v96
	v_fmac_f32_e32 v82, v97, v97
	v_fmac_f32_e32 v83, v95, v95
	v_add_f32_e32 v82, v82, v83
	v_add_f32_e32 v82, v82, v91
	ds_bpermute_b32 v83, v1, v82
	v_cvt_pk_bf16_f32 v91, v92, v93
	global_store_dwordx2 v[102:103], v[90:91], off offset:32
	v_cvt_pk_bf16_f32 v84, v86, v87
	v_cvt_pk_bf16_f32 v85, v88, v89
	s_waitcnt lgkmcnt(0)
	v_add_f32_e32 v82, v82, v83
	ds_bpermute_b32 v83, v233, v82
	global_store_dwordx2 v[102:103], v[84:85], off offset:256
	v_cvt_pk_bf16_f32 v84, v97, v99
	v_cvt_pk_bf16_f32 v85, v95, v96
	global_store_dwordx2 v[102:103], v[84:85], off offset:288
	v_lshl_add_u64 v[236:237], v[236:237], 0, v[238:239]
	global_load_dwordx4 v[162:165], v[236:237], off
	global_load_dwordx4 v[166:169], v[236:237], off offset:64
	global_load_dwordx4 v[170:173], v[236:237], off offset:512
	global_load_dwordx4 v[174:177], v[236:237], off offset:576
	s_and_saveexec_b64 s[2:3], s[4:5]
	s_cbranch_execz .LBB0_264
	v_lshl_add_u32 v84, v98, 4, s31
	s_waitcnt lgkmcnt(0)
	v_add_f32_e32 v82, v82, v83
	ds_write_b32 v84, v82 offset:16384
.LBB0_264:
	s_or_b64 exec, exec, s[2:3]
	ds_read_b32 v84, v210 offset:8384
	v_or_b32_e32 v82, 48, v225
	v_add_u32_e32 v86, s30, v82
	v_ashrrev_i32_e32 v87, 31, v86
	s_waitcnt lgkmcnt(0)
	v_pk_mul_f32 v[80:81], v[80:81], v[84:85] op_sel_hi:[1,0]
	s_nop 0
	v_pk_fma_f32 v[80:81], v[144:145], v[80:81], v[160:161]
	v_pk_mul_f32 v[78:79], v[78:79], v[84:85] op_sel_hi:[1,0]
	v_cndmask_b32_e32 v83, v80, v94, vcc
	v_cndmask_b32_e32 v85, v81, v94, vcc
	v_lshlrev_b64 v[80:81], 11, v[86:87]
	v_pk_fma_f32 v[78:79], v[142:143], v[78:79], v[158:159]
	v_lshl_add_u64 v[80:81], s[0:1], 0, v[80:81]
	v_cndmask_b32_e32 v88, v78, v94, vcc
	v_cndmask_b32_e32 v89, v79, v94, vcc
	v_cvt_pk_bf16_f32 v78, v88, v89
	v_cvt_pk_bf16_f32 v79, v83, v85
	v_lshl_add_u64 v[80:81], v[214:215], 1, v[80:81]
	v_pk_mul_f32 v[74:75], v[74:75], v[84:85] op_sel_hi:[1,0]
	global_store_dwordx2 v[80:81], v[78:79], off
	v_mul_f32_e32 v78, v89, v89
	v_mul_f32_e32 v79, v85, v85
	v_pk_mul_f32 v[76:77], v[76:77], v[84:85] op_sel_hi:[1,0]
	v_pk_fma_f32 v[74:75], v[134:135], v[74:75], v[154:155]
	v_fmac_f32_e32 v78, v88, v88
	v_fmac_f32_e32 v79, v83, v83
	v_pk_fma_f32 v[76:77], v[136:137], v[76:77], v[156:157]
	v_cndmask_b32_e32 v75, v75, v94, vcc
	v_add_f32_e32 v78, v78, v79
	v_cndmask_b32_e32 v77, v77, v94, vcc
	v_cndmask_b32_e32 v79, v74, v94, vcc
	v_cvt_pk_bf16_f32 v74, v79, v75
	v_mul_f32_e32 v75, v75, v75
	v_cndmask_b32_e32 v76, v76, v94, vcc
	v_fmac_f32_e32 v75, v79, v79
	v_mul_f32_e32 v79, v77, v77
	v_pk_mul_f32 v[72:73], v[72:73], v[84:85] op_sel_hi:[1,0]
	v_pk_mul_f32 v[70:71], v[70:71], v[84:85] op_sel_hi:[1,0]
	v_fmac_f32_e32 v79, v76, v76
	v_pk_fma_f32 v[72:73], v[132:133], v[72:73], v[152:153]
	v_pk_fma_f32 v[70:71], v[130:131], v[70:71], v[150:151]
	v_add_f32_e32 v75, v75, v79
	v_cndmask_b32_e32 v73, v73, v94, vcc
	v_cndmask_b32_e32 v71, v71, v94, vcc
	v_add_f32_e32 v75, v78, v75
	v_cndmask_b32_e32 v72, v72, v94, vcc
	v_cndmask_b32_e32 v70, v70, v94, vcc
	v_mul_f32_e32 v78, v71, v71
	v_mul_f32_e32 v79, v73, v73
	v_pk_mul_f32 v[68:69], v[68:69], v[84:85] op_sel_hi:[1,0]
	v_pk_mul_f32 v[66:67], v[66:67], v[84:85] op_sel_hi:[1,0]
	v_fmac_f32_e32 v78, v70, v70
	v_fmac_f32_e32 v79, v72, v72
	v_pk_fma_f32 v[68:69], v[124:125], v[68:69], v[148:149]
	v_pk_fma_f32 v[66:67], v[122:123], v[66:67], v[146:147]
	v_add_f32_e32 v78, v78, v79
	v_cndmask_b32_e32 v79, v69, v94, vcc
	v_cndmask_b32_e32 v84, v67, v94, vcc
	v_add_f32_e32 v75, v78, v75
	v_cndmask_b32_e32 v78, v68, v94, vcc
	v_cndmask_b32_e32 v83, v66, v94, vcc
	v_mul_f32_e32 v66, v84, v84
	v_mul_f32_e32 v67, v79, v79
	v_fmac_f32_e32 v66, v83, v83
	v_fmac_f32_e32 v67, v78, v78
	v_add_f32_e32 v66, v66, v67
	v_add_f32_e32 v66, v66, v75
	ds_bpermute_b32 v67, v1, v66
	v_cvt_pk_bf16_f32 v75, v76, v77
	global_store_dwordx2 v[80:81], v[74:75], off offset:32
	v_cvt_pk_bf16_f32 v68, v70, v71
	v_cvt_pk_bf16_f32 v69, v72, v73
	s_waitcnt lgkmcnt(0)
	v_add_f32_e32 v66, v66, v67
	ds_bpermute_b32 v67, v233, v66
	global_store_dwordx2 v[80:81], v[68:69], off offset:256
	v_cvt_pk_bf16_f32 v68, v83, v84
	v_cvt_pk_bf16_f32 v69, v78, v79
	global_store_dwordx2 v[80:81], v[68:69], off offset:288
	v_lshl_add_u64 v[236:237], v[236:237], 0, v[238:239]
	global_load_dwordx4 v[146:149], v[236:237], off
	global_load_dwordx4 v[150:153], v[236:237], off offset:64
	global_load_dwordx4 v[154:157], v[236:237], off offset:512
	global_load_dwordx4 v[158:161], v[236:237], off offset:576
	s_and_saveexec_b64 s[2:3], s[4:5]
	s_cbranch_execz .LBB0_266
	v_lshl_add_u32 v68, v82, 4, s31
	s_waitcnt lgkmcnt(0)
	v_add_f32_e32 v66, v66, v67
	ds_write_b32 v68, v66 offset:16384
.LBB0_266:
	s_or_b64 exec, exec, s[2:3]
	s_add_i32 s2, s28, 0x80
	v_or_b32_e32 v66, s2, v219
	v_add_u32_e32 v74, s30, v66
	v_ashrrev_i32_e32 v75, 31, v74
	v_lshlrev_b64 v[68:69], 12, v[74:75]
	v_lshl_add_u64 v[76:77], v[216:217], 0, v[68:69]
	s_waitcnt lgkmcnt(0)
	v_add_u32_e32 v67, s28, v219
	v_lshl_add_u32 v67, v67, 2, 0
	ds_read_b32 v78, v67 offset:8704
	v_lshlrev_b64 v[74:75], 10, v[74:75]
	v_lshl_add_u64 v[74:75], v[74:75], 0, v[214:215]
	v_mov_b32_e32 v68, 0x7fc00000
	v_lshl_add_u64 v[74:75], v[74:75], 1, s[0:1]
	s_waitcnt lgkmcnt(0)
	v_pk_mul_f32 v[64:65], v[64:65], v[78:79] op_sel_hi:[1,0]
	v_pk_mul_f32 v[62:63], v[62:63], v[78:79] op_sel_hi:[1,0]
	v_pk_mul_f32 v[60:61], v[60:61], v[78:79] op_sel_hi:[1,0]
	v_pk_mul_f32 v[58:59], v[58:59], v[78:79] op_sel_hi:[1,0]
	v_pk_mul_f32 v[56:57], v[56:57], v[78:79] op_sel_hi:[1,0]
	v_pk_mul_f32 v[54:55], v[54:55], v[78:79] op_sel_hi:[1,0]
	v_pk_mul_f32 v[52:53], v[52:53], v[78:79] op_sel_hi:[1,0]
	v_pk_mul_f32 v[50:51], v[50:51], v[78:79] op_sel_hi:[1,0]
	s_waitcnt vmcnt(24)
	v_pk_fma_f32 v[64:65], v[144:145], v[64:65], v[196:197]
	v_pk_fma_f32 v[62:63], v[142:143], v[62:63], v[194:195]
	v_cndmask_b32_e32 v69, v64, v68, vcc
	v_cndmask_b32_e32 v70, v65, v68, vcc
	v_cndmask_b32_e32 v71, v62, v68, vcc
	v_cndmask_b32_e32 v72, v63, v68, vcc
	v_cvt_pk_bf16_f32 v62, v71, v72
	v_cvt_pk_bf16_f32 v63, v69, v70
	global_store_dwordx2 v[74:75], v[62:63], off
	v_mul_f32_e32 v72, v72, v72
	v_mul_f32_e32 v70, v70, v70
	v_fmac_f32_e32 v72, v71, v71
	v_fmac_f32_e32 v70, v69, v69
	v_add_f32_e32 v69, v72, v70
	v_pk_fma_f32 v[60:61], v[136:137], v[60:61], v[200:201]
	v_pk_fma_f32 v[58:59], v[134:135], v[58:59], v[198:199]
	v_cndmask_b32_e32 v62, v60, v68, vcc
	v_cndmask_b32_e32 v63, v61, v68, vcc
	v_cndmask_b32_e32 v64, v58, v68, vcc
	v_cndmask_b32_e32 v65, v59, v68, vcc
	v_cvt_pk_bf16_f32 v58, v64, v65
	v_cvt_pk_bf16_f32 v59, v62, v63
	global_store_dwordx2 v[74:75], v[58:59], off offset:32
	v_mul_f32_e32 v65, v65, v65
	v_mul_f32_e32 v63, v63, v63
	v_fmac_f32_e32 v65, v64, v64
	v_fmac_f32_e32 v63, v62, v62
	v_add_f32_e32 v62, v65, v63
	v_add_f32_e32 v62, v69, v62
	v_pk_fma_f32 v[56:57], v[132:133], v[56:57], v[204:205]
	v_pk_fma_f32 v[54:55], v[130:131], v[54:55], v[202:203]
	v_cndmask_b32_e32 v58, v56, v68, vcc
	v_cndmask_b32_e32 v59, v57, v68, vcc
	v_cndmask_b32_e32 v60, v54, v68, vcc
	v_cndmask_b32_e32 v61, v55, v68, vcc
	v_cvt_pk_bf16_f32 v54, v60, v61
	v_cvt_pk_bf16_f32 v55, v58, v59
	global_store_dwordx2 v[74:75], v[54:55], off offset:256
	v_mul_f32_e32 v61, v61, v61
	v_mul_f32_e32 v59, v59, v59
	v_fmac_f32_e32 v61, v60, v60
	v_fmac_f32_e32 v59, v58, v58
	v_add_f32_e32 v58, v61, v59
	v_add_f32_e32 v58, v62, v58
	v_pk_fma_f32 v[52:53], v[124:125], v[52:53], v[208:209]
	v_pk_fma_f32 v[50:51], v[122:123], v[50:51], v[206:207]
	v_cndmask_b32_e32 v53, v53, v68, vcc
	v_cndmask_b32_e32 v55, v51, v68, vcc
	v_cndmask_b32_e32 v54, v52, v68, vcc
	v_cndmask_b32_e32 v52, v50, v68, vcc
	v_mul_f32_e32 v50, v55, v55
	v_mul_f32_e32 v51, v53, v53
	v_fmac_f32_e32 v50, v52, v52
	v_fmac_f32_e32 v51, v54, v54
	v_add_f32_e32 v50, v50, v51
	v_add_f32_e32 v50, v58, v50
	ds_bpermute_b32 v51, v1, v50
	v_cvt_pk_bf16_f32 v52, v52, v55
	v_cvt_pk_bf16_f32 v53, v54, v53
	global_store_dwordx2 v[74:75], v[52:53], off offset:288
	s_waitcnt lgkmcnt(0)
	v_add_f32_e32 v50, v50, v51
	ds_bpermute_b32 v51, v233, v50
	s_and_saveexec_b64 s[2:3], s[4:5]
	s_cbranch_execz .LBB0_268
	v_lshl_add_u32 v52, v66, 4, s31
	s_waitcnt lgkmcnt(0)
	v_add_f32_e32 v50, v50, v51
	ds_write_b32 v52, v50 offset:16384
.LBB0_268:
	s_or_b64 exec, exec, s[2:3]
	v_or_b32_e32 v50, 16, v66
	v_add_u32_e32 v56, s30, v50
	v_ashrrev_i32_e32 v57, 31, v56
	v_lshlrev_b64 v[52:53], 12, v[56:57]
	v_lshl_add_u64 v[58:59], v[216:217], 0, v[52:53]
	ds_read_b32 v60, v67 offset:8768
	v_lshlrev_b64 v[56:57], 10, v[56:57]
	v_lshl_add_u64 v[56:57], v[56:57], 0, v[214:215]
	v_lshl_add_u64 v[56:57], v[56:57], 1, s[0:1]
	s_waitcnt lgkmcnt(0)
	v_pk_mul_f32 v[48:49], v[48:49], v[60:61] op_sel_hi:[1,0]
	v_pk_mul_f32 v[46:47], v[46:47], v[60:61] op_sel_hi:[1,0]
	v_pk_mul_f32 v[44:45], v[44:45], v[60:61] op_sel_hi:[1,0]
	v_pk_mul_f32 v[42:43], v[42:43], v[60:61] op_sel_hi:[1,0]
	v_pk_mul_f32 v[40:41], v[40:41], v[60:61] op_sel_hi:[1,0]
	v_pk_mul_f32 v[38:39], v[38:39], v[60:61] op_sel_hi:[1,0]
	v_pk_mul_f32 v[36:37], v[36:37], v[60:61] op_sel_hi:[1,0]
	v_pk_mul_f32 v[34:35], v[34:35], v[60:61] op_sel_hi:[1,0]
	s_waitcnt vmcnt(20)
	v_pk_fma_f32 v[48:49], v[144:145], v[48:49], v[180:181]
	v_pk_fma_f32 v[46:47], v[142:143], v[46:47], v[178:179]
	v_cndmask_b32_e32 v51, v48, v68, vcc
	v_cndmask_b32_e32 v52, v49, v68, vcc
	v_cndmask_b32_e32 v53, v46, v68, vcc
	v_cndmask_b32_e32 v54, v47, v68, vcc
	v_cvt_pk_bf16_f32 v46, v53, v54
	v_cvt_pk_bf16_f32 v47, v51, v52
	global_store_dwordx2 v[56:57], v[46:47], off
	v_mul_f32_e32 v54, v54, v54
	v_mul_f32_e32 v52, v52, v52
	v_fmac_f32_e32 v54, v53, v53
	v_fmac_f32_e32 v52, v51, v51
	v_add_f32_e32 v51, v54, v52
	v_pk_fma_f32 v[44:45], v[136:137], v[44:45], v[184:185]
	v_pk_fma_f32 v[42:43], v[134:135], v[42:43], v[182:183]
	v_cndmask_b32_e32 v46, v44, v68, vcc
	v_cndmask_b32_e32 v47, v45, v68, vcc
	v_cndmask_b32_e32 v48, v42, v68, vcc
	v_cndmask_b32_e32 v49, v43, v68, vcc
	v_cvt_pk_bf16_f32 v42, v48, v49
	v_cvt_pk_bf16_f32 v43, v46, v47
	global_store_dwordx2 v[56:57], v[42:43], off offset:32
	v_mul_f32_e32 v49, v49, v49
	v_mul_f32_e32 v47, v47, v47
	v_fmac_f32_e32 v49, v48, v48
	v_fmac_f32_e32 v47, v46, v46
	v_add_f32_e32 v46, v49, v47
	v_add_f32_e32 v46, v51, v46
	v_pk_fma_f32 v[40:41], v[132:133], v[40:41], v[188:189]
	v_pk_fma_f32 v[38:39], v[130:131], v[38:39], v[186:187]
	v_cndmask_b32_e32 v42, v40, v68, vcc
	v_cndmask_b32_e32 v43, v41, v68, vcc
	v_cndmask_b32_e32 v44, v38, v68, vcc
	v_cndmask_b32_e32 v45, v39, v68, vcc
	v_cvt_pk_bf16_f32 v38, v44, v45
	v_cvt_pk_bf16_f32 v39, v42, v43
	global_store_dwordx2 v[56:57], v[38:39], off offset:256
	v_mul_f32_e32 v45, v45, v45
	v_mul_f32_e32 v43, v43, v43
	v_fmac_f32_e32 v45, v44, v44
	v_fmac_f32_e32 v43, v42, v42
	v_add_f32_e32 v42, v45, v43
	v_add_f32_e32 v42, v46, v42
	v_pk_fma_f32 v[36:37], v[124:125], v[36:37], v[192:193]
	v_pk_fma_f32 v[34:35], v[122:123], v[34:35], v[190:191]
	v_cndmask_b32_e32 v37, v37, v68, vcc
	v_cndmask_b32_e32 v39, v35, v68, vcc
	v_cndmask_b32_e32 v38, v36, v68, vcc
	v_cndmask_b32_e32 v36, v34, v68, vcc
	v_mul_f32_e32 v34, v39, v39
	v_mul_f32_e32 v35, v37, v37
	v_fmac_f32_e32 v34, v36, v36
	v_fmac_f32_e32 v35, v38, v38
	v_add_f32_e32 v34, v34, v35
	v_add_f32_e32 v34, v42, v34
	ds_bpermute_b32 v35, v1, v34
	v_cvt_pk_bf16_f32 v36, v36, v39
	v_cvt_pk_bf16_f32 v37, v38, v37
	global_store_dwordx2 v[56:57], v[36:37], off offset:288
	s_waitcnt lgkmcnt(0)
	v_add_f32_e32 v34, v34, v35
	ds_bpermute_b32 v35, v233, v34
	s_and_saveexec_b64 s[2:3], s[4:5]
	s_cbranch_execz .LBB0_270
	v_lshl_add_u32 v36, v50, 4, s31
	s_waitcnt lgkmcnt(0)
	v_add_f32_e32 v34, v34, v35
	ds_write_b32 v36, v34 offset:16384
.LBB0_270:
	s_or_b64 exec, exec, s[2:3]
	s_waitcnt lgkmcnt(0)
	v_or_b32_e32 v35, 32, v66
	v_add_u32_e32 v40, s30, v35
	v_ashrrev_i32_e32 v41, 31, v40
	v_lshlrev_b64 v[36:37], 12, v[40:41]
	v_lshl_add_u64 v[42:43], v[216:217], 0, v[36:37]
	ds_read_b32 v44, v210 offset:8832
	v_lshlrev_b64 v[40:41], 10, v[40:41]
	v_lshl_add_u64 v[40:41], v[40:41], 0, v[214:215]
	v_mov_b32_e32 v34, 0x7fc00000
	v_lshl_add_u64 v[40:41], v[40:41], 1, s[0:1]
	s_waitcnt lgkmcnt(0)
	v_pk_mul_f32 v[32:33], v[32:33], v[44:45] op_sel_hi:[1,0]
	v_pk_mul_f32 v[30:31], v[30:31], v[44:45] op_sel_hi:[1,0]
	v_pk_mul_f32 v[28:29], v[28:29], v[44:45] op_sel_hi:[1,0]
	v_pk_mul_f32 v[26:27], v[26:27], v[44:45] op_sel_hi:[1,0]
	v_pk_mul_f32 v[24:25], v[24:25], v[44:45] op_sel_hi:[1,0]
	v_pk_mul_f32 v[22:23], v[22:23], v[44:45] op_sel_hi:[1,0]
	v_pk_mul_f32 v[20:21], v[20:21], v[44:45] op_sel_hi:[1,0]
	v_pk_mul_f32 v[18:19], v[18:19], v[44:45] op_sel_hi:[1,0]
	s_waitcnt vmcnt(16)
	v_pk_fma_f32 v[32:33], v[144:145], v[32:33], v[164:165]
	v_pk_fma_f32 v[30:31], v[142:143], v[30:31], v[162:163]
	v_cndmask_b32_e32 v36, v32, v34, vcc
	v_cndmask_b32_e32 v37, v33, v34, vcc
	v_cndmask_b32_e32 v38, v30, v34, vcc
	v_cndmask_b32_e32 v39, v31, v34, vcc
	v_cvt_pk_bf16_f32 v30, v38, v39
	v_cvt_pk_bf16_f32 v31, v36, v37
	global_store_dwordx2 v[40:41], v[30:31], off
	v_mul_f32_e32 v39, v39, v39
	v_mul_f32_e32 v37, v37, v37
	v_fmac_f32_e32 v39, v38, v38
	v_fmac_f32_e32 v37, v36, v36
	v_add_f32_e32 v36, v39, v37
	v_pk_fma_f32 v[28:29], v[136:137], v[28:29], v[168:169]
	v_pk_fma_f32 v[26:27], v[134:135], v[26:27], v[166:167]
	v_cndmask_b32_e32 v30, v28, v34, vcc
	v_cndmask_b32_e32 v31, v29, v34, vcc
	v_cndmask_b32_e32 v32, v26, v34, vcc
	v_cndmask_b32_e32 v33, v27, v34, vcc
	v_cvt_pk_bf16_f32 v26, v32, v33
	v_cvt_pk_bf16_f32 v27, v30, v31
	global_store_dwordx2 v[40:41], v[26:27], off offset:32
	v_mul_f32_e32 v33, v33, v33
	v_mul_f32_e32 v31, v31, v31
	v_fmac_f32_e32 v33, v32, v32
	v_fmac_f32_e32 v31, v30, v30
	v_add_f32_e32 v30, v33, v31
	v_add_f32_e32 v30, v36, v30
	v_pk_fma_f32 v[24:25], v[132:133], v[24:25], v[172:173]
	v_pk_fma_f32 v[22:23], v[130:131], v[22:23], v[170:171]
	v_cndmask_b32_e32 v26, v24, v34, vcc
	v_cndmask_b32_e32 v27, v25, v34, vcc
	v_cndmask_b32_e32 v28, v22, v34, vcc
	v_cndmask_b32_e32 v29, v23, v34, vcc
	v_cvt_pk_bf16_f32 v22, v28, v29
	v_cvt_pk_bf16_f32 v23, v26, v27
	global_store_dwordx2 v[40:41], v[22:23], off offset:256
	v_mul_f32_e32 v29, v29, v29
	v_mul_f32_e32 v27, v27, v27
	v_fmac_f32_e32 v29, v28, v28
	v_fmac_f32_e32 v27, v26, v26
	v_add_f32_e32 v26, v29, v27
	v_add_f32_e32 v26, v30, v26
	v_pk_fma_f32 v[20:21], v[124:125], v[20:21], v[176:177]
	v_pk_fma_f32 v[18:19], v[122:123], v[18:19], v[174:175]
	v_cndmask_b32_e32 v21, v21, v34, vcc
	v_cndmask_b32_e32 v23, v19, v34, vcc
	v_cndmask_b32_e32 v22, v20, v34, vcc
	v_cndmask_b32_e32 v20, v18, v34, vcc
	v_mul_f32_e32 v18, v23, v23
	v_mul_f32_e32 v19, v21, v21
	v_fmac_f32_e32 v18, v20, v20
	v_fmac_f32_e32 v19, v22, v22
	v_add_f32_e32 v18, v18, v19
	v_add_f32_e32 v18, v26, v18
	ds_bpermute_b32 v19, v1, v18
	v_cvt_pk_bf16_f32 v20, v20, v23
	v_cvt_pk_bf16_f32 v21, v22, v21
	global_store_dwordx2 v[40:41], v[20:21], off offset:288
	s_waitcnt lgkmcnt(0)
	v_add_f32_e32 v18, v18, v19
	ds_bpermute_b32 v19, v233, v18
	s_and_saveexec_b64 s[2:3], s[4:5]
	s_cbranch_execz .LBB0_272
	v_lshl_add_u32 v20, v35, 4, s31
	s_waitcnt lgkmcnt(0)
	v_add_f32_e32 v18, v18, v19
	ds_write_b32 v20, v18 offset:16384
.LBB0_272:
	s_or_b64 exec, exec, s[2:3]
	v_or_b32_e32 v18, 48, v66
	v_add_u32_e32 v24, s30, v18
	v_ashrrev_i32_e32 v25, 31, v24
	v_lshlrev_b64 v[20:21], 12, v[24:25]
	v_lshl_add_u64 v[26:27], v[216:217], 0, v[20:21]
	ds_read_b32 v28, v67 offset:8896
	v_lshlrev_b64 v[24:25], 10, v[24:25]
	v_lshl_add_u64 v[24:25], v[24:25], 0, v[214:215]
	v_lshl_add_u64 v[24:25], v[24:25], 1, s[0:1]
	s_waitcnt lgkmcnt(0)
	v_pk_mul_f32 v[16:17], v[16:17], v[28:29] op_sel_hi:[1,0]
	v_pk_mul_f32 v[14:15], v[14:15], v[28:29] op_sel_hi:[1,0]
	v_pk_mul_f32 v[12:13], v[12:13], v[28:29] op_sel_hi:[1,0]
	v_pk_mul_f32 v[10:11], v[10:11], v[28:29] op_sel_hi:[1,0]
	v_pk_mul_f32 v[8:9], v[8:9], v[28:29] op_sel_hi:[1,0]
	v_pk_mul_f32 v[6:7], v[6:7], v[28:29] op_sel_hi:[1,0]
	v_pk_mul_f32 v[4:5], v[4:5], v[28:29] op_sel_hi:[1,0]
	v_pk_mul_f32 v[2:3], v[2:3], v[28:29] op_sel_hi:[1,0]
	s_waitcnt vmcnt(12)
	v_pk_fma_f32 v[16:17], v[144:145], v[16:17], v[148:149]
	v_pk_fma_f32 v[14:15], v[142:143], v[14:15], v[146:147]
	v_cndmask_b32_e32 v19, v16, v34, vcc
	v_cndmask_b32_e32 v20, v17, v34, vcc
	v_cndmask_b32_e32 v21, v14, v34, vcc
	v_cndmask_b32_e32 v22, v15, v34, vcc
	v_cvt_pk_bf16_f32 v14, v21, v22
	v_cvt_pk_bf16_f32 v15, v19, v20
	global_store_dwordx2 v[24:25], v[14:15], off
	v_mul_f32_e32 v22, v22, v22
	v_mul_f32_e32 v20, v20, v20
	v_fmac_f32_e32 v22, v21, v21
	v_fmac_f32_e32 v20, v19, v19
	v_add_f32_e32 v19, v22, v20
	v_pk_fma_f32 v[12:13], v[136:137], v[12:13], v[152:153]
	v_pk_fma_f32 v[10:11], v[134:135], v[10:11], v[150:151]
	v_cndmask_b32_e32 v14, v12, v34, vcc
	v_cndmask_b32_e32 v15, v13, v34, vcc
	v_cndmask_b32_e32 v16, v10, v34, vcc
	v_cndmask_b32_e32 v17, v11, v34, vcc
	v_cvt_pk_bf16_f32 v10, v16, v17
	v_cvt_pk_bf16_f32 v11, v14, v15
	global_store_dwordx2 v[24:25], v[10:11], off offset:32
	v_mul_f32_e32 v17, v17, v17
	v_mul_f32_e32 v15, v15, v15
	v_fmac_f32_e32 v17, v16, v16
	v_fmac_f32_e32 v15, v14, v14
	v_add_f32_e32 v14, v17, v15
	v_add_f32_e32 v14, v19, v14
	v_pk_fma_f32 v[8:9], v[132:133], v[8:9], v[156:157]
	v_pk_fma_f32 v[6:7], v[130:131], v[6:7], v[154:155]
	v_cndmask_b32_e32 v10, v8, v34, vcc
	v_cndmask_b32_e32 v11, v9, v34, vcc
	v_cndmask_b32_e32 v12, v6, v34, vcc
	v_cndmask_b32_e32 v13, v7, v34, vcc
	v_cvt_pk_bf16_f32 v6, v12, v13
	v_cvt_pk_bf16_f32 v7, v10, v11
	global_store_dwordx2 v[24:25], v[6:7], off offset:256
	v_mul_f32_e32 v13, v13, v13
	v_mul_f32_e32 v11, v11, v11
	v_fmac_f32_e32 v13, v12, v12
	v_fmac_f32_e32 v11, v10, v10
	v_add_f32_e32 v10, v13, v11
	v_add_f32_e32 v10, v14, v10
	v_pk_fma_f32 v[4:5], v[124:125], v[4:5], v[160:161]
	v_pk_fma_f32 v[2:3], v[122:123], v[2:3], v[158:159]
	v_cndmask_b32_e32 v5, v5, v34, vcc
	v_cndmask_b32_e32 v7, v3, v34, vcc
	v_cndmask_b32_e32 v6, v4, v34, vcc
	v_cndmask_b32_e32 v4, v2, v34, vcc
	v_mul_f32_e32 v2, v7, v7
	v_mul_f32_e32 v3, v5, v5
	v_fmac_f32_e32 v2, v4, v4
	v_fmac_f32_e32 v3, v6, v6
	v_add_f32_e32 v2, v2, v3
	v_add_f32_e32 v2, v10, v2
	ds_bpermute_b32 v3, v1, v2
	v_cvt_pk_bf16_f32 v4, v4, v7
	v_cvt_pk_bf16_f32 v5, v6, v5
	global_store_dwordx2 v[24:25], v[4:5], off offset:288
	s_waitcnt lgkmcnt(0)
	v_add_f32_e32 v2, v2, v3
	ds_bpermute_b32 v3, v233, v2
	s_and_saveexec_b64 s[0:1], s[4:5]
	s_cbranch_execz .LBB0_274
	v_lshl_add_u32 v4, v18, 4, s31
	s_waitcnt lgkmcnt(0)
	v_add_f32_e32 v2, v2, v3
	ds_write_b32 v4, v2 offset:16384
